# previous best + static priority raise (s_setprio 1) for waves 4-7 during the prompt-attention item
# speedup vs baseline: 1.0199x; 1.0005x over previous
.LBB0_483:
	s_and_b64 vcc, exec, s[0:1]
	s_cbranch_vccz .LBB0_598
	s_and_b32 s0, s5, 0xffff
	s_mul_i32 s0, s0, 0xaaab
	s_lshr_b32 s39, s0, 21
	s_mul_i32 s0, s39, 48
	s_sub_i32 s0, s5, s0
	s_and_b32 s1, s0, 0xff
	s_mulk_i32 s1, 0xab
	s_load_dwordx4 s[12:15], s[52:53], 0x80
	s_bfe_u32 s2, s1, 0x5000b
	s_mul_i32 s3, s2, 12
	v_mov_b32_e32 v4, v0
	s_sub_i32 s0, s0, s3
	s_sub_i32 s42, 7, s39
	v_readfirstlane_b32 s40, v4
	s_and_b32 s44, s0, 0xff
	s_ashr_i32 s66, s40, 6
	s_cmp_lt_u32 s66, 4
	s_cbranch_scc1 .Lpa_np
	s_setprio 1
.Lpa_np:
	s_mov_b64 s[6:7], 0
	s_waitcnt lgkmcnt(0)
	s_add_u32 s36, s12, s6
	s_addc_u32 s37, s13, s7
	s_add_u32 s68, s36, 0x4c00000
	v_and_b32_e32 v212, 31, v4
	s_addc_u32 s69, s37, 0
	s_lshl_b32 s41, s42, 8
	s_and_b32 s0, s1, 0xf800
	s_or_b32 s5, s0, s41
	v_lshlrev_b32_e32 v3, 3, v212
	v_or_b32_e32 v5, s5, v3
	v_add_u32_e32 v5, s66, v5
	v_mov_b64_e32 v[6:7], s[68:69]
	v_mad_i64_i32 v[6:7], s[0:1], v5, s19, v[6:7]
	v_bfe_u32 v211, v4, 5, 1
	s_lshl_b32 s0, s44, 8
	s_mov_b32 s1, s21
	v_lshl_add_u64 v[6:7], v[6:7], 0, s[0:1]
	v_lshlrev_b32_e32 v198, 4, v211
	v_mov_b32_e32 v199, v2
	v_lshl_add_u64 v[6:7], v[6:7], 0, v[198:199]
	s_lshl_b32 s43, s66, 2
	v_bfe_u32 v197, v4, 4, 2
	global_load_dwordx4 v[162:165], v[6:7], off
	global_load_dwordx4 v[166:169], v[6:7], off offset:32
	global_load_dwordx4 v[170:173], v[6:7], off offset:64
	global_load_dwordx4 v[174:177], v[6:7], off offset:96
	global_load_dwordx4 v[178:181], v[6:7], off offset:128
	global_load_dwordx4 v[182:185], v[6:7], off offset:160
	global_load_dwordx4 v[186:189], v[6:7], off offset:192
	global_load_dwordx4 v[190:193], v[6:7], off offset:224
	v_or_b32_e32 v5, s43, v197
	v_lshlrev_b32_e32 v6, 4, v4
	v_and_b32_e32 v6, 0xf0, v6
	v_lshlrev_b32_e32 v7, 4, v5
	s_movk_i32 s0, 0x70
	v_bitop3_b32 v6, v7, v6, s0 bitop3:0x6c
	s_ashr_i32 s1, s40, 4
	v_lshrrev_b32_e32 v8, 1, v6
	s_and_b32 s3, s1, 0x3ffffff0
	v_lshrrev_b32_e32 v6, 2, v4
	v_lshrrev_b32_e32 v199, 1, v4
	s_lshr_b32 s1, s1, 1
	s_lshl_b32 s0, s66, 1
	v_and_or_b32 v6, v6, 3, s3
	v_and_b32_e32 v7, 8, v199
	s_and_b32 s1, s1, 4
	s_lshl_b32 s20, s44, 7
	v_or3_b32 v6, v6, v7, s1
	v_and_or_b32 v7, s0, 2, v211
	v_lshlrev_b32_e32 v210, 3, v4
	v_lshlrev_b32_e32 v7, 5, v7
	v_and_b32_e32 v9, 24, v210
	s_add_i32 s0, s20, 0xc00
	s_ashr_i32 s67, s66, 31
	v_lshlrev_b32_e32 v10, 2, v6
	v_or3_b32 v6, v7, v9, s0
	v_mov_b32_e32 v7, v2
	s_movk_i32 s3, 0x1800
	s_mul_i32 s2, s2, 0x1800000
	v_mad_i64_i32 v[200:201], s[0:1], v10, s3, v[6:7]
	s_add_u32 s70, s68, s2
	v_lshlrev_b32_e32 v5, 2, v5
	s_addc_u32 s71, s69, 0
	s_lshl_b32 s0, s66, 10
	v_mov_b64_e32 v[6:7], s[20:21]
	s_add_i32 s38, s0, 0
	v_mad_i64_i32 v[202:203], s[0:1], v5, s3, v[6:7]
	v_or_b32_e32 v202, v202, v8
	v_lshl_add_u64 v[6:7], v[202:203], 1, s[70:71]
	s_mov_b64 s[0:1], 0xc00
	v_lshl_add_u64 v[8:9], v[6:7], 0, s[0:1]
	s_add_i32 s0, s38, 0x8000
	s_mov_b32 m0, s38
	v_lshl_add_u64 v[10:11], v[200:201], 1, s[70:71]
	global_load_lds_dwordx4 v[8:9], off
	s_mov_b32 m0, s0
	s_mov_b64 s[0:1], 0x3c00
	global_load_lds_dwordx4 v[10:11], off
	v_lshl_add_u64 v[8:9], v[6:7], 0, s[0:1]
	s_add_i32 m0, s38, 0x2000
	s_mov_b64 s[0:1], 0x3000
	global_load_lds_dwordx4 v[8:9], off
	v_lshl_add_u64 v[8:9], v[10:11], 0, s[0:1]
	s_add_i32 m0, s38, 0xa000
	s_mov_b64 s[0:1], 0x6c00
	global_load_lds_dwordx4 v[8:9], off
	v_lshl_add_u64 v[8:9], v[6:7], 0, s[0:1]
	s_add_i32 m0, s38, 0x4000
	s_mov_b64 s[0:1], 0x6000
	global_load_lds_dwordx4 v[8:9], off
	v_lshl_add_u64 v[8:9], v[10:11], 0, s[0:1]
	s_add_i32 m0, s38, 0xc000
	s_mov_b64 s[0:1], 0x9c00
	global_load_lds_dwordx4 v[8:9], off
	v_lshl_add_u64 v[6:7], v[6:7], 0, s[0:1]
	s_add_i32 m0, s38, 0x6000
	s_mov_b64 s[0:1], 0x9000
	global_load_lds_dwordx4 v[6:7], off
	v_lshl_add_u64 v[6:7], v[10:11], 0, s[0:1]
	s_add_i32 m0, s38, 0xe000
	s_movk_i32 s0, 0xa80
	global_load_lds_dwordx4 v[6:7], off
	v_cmp_gt_i32_e32 vcc, s0, v4
	s_and_saveexec_b64 s[0:1], vcc
	s_cbranch_execz .LBB0_497
	v_max_i32_e32 v5, 0x880, v4
	v_sub_u32_e32 v5, v5, v4
	v_add_u32_e32 v5, 0x1ff, v5
	s_movk_i32 s2, 0x1ff
	v_cmp_lt_u32_e32 vcc, s2, v5
	s_mov_b64 s[2:3], -1
	v_mov_b32_e32 v6, v4
	s_and_saveexec_b64 s[12:13], vcc
	s_cbranch_execz .LBB0_494
	s_mul_i32 s2, s44, 0x2a00
	v_lshrrev_b32_e32 v8, 9, v5
	s_add_u32 s2, s36, s2
	s_addc_u32 s3, s37, 0
	v_add_u32_e32 v6, -1, v8
	s_add_u32 s14, s2, 0x2900000
	v_add_u32_e32 v5, 0x200, v4
	v_lshrrev_b32_e32 v7, 1, v6
	s_addc_u32 s15, s3, 0
	v_add_u32_e32 v9, 1, v7
	v_cmp_lt_u32_e32 vcc, 13, v6
	v_mov_b32_e32 v12, 0
	v_mov_b64_e32 v[6:7], v[4:5]
	s_and_saveexec_b64 s[24:25], vcc
	s_cbranch_execz .LBB0_490
	v_and_b32_e32 v10, -8, v9
	v_lshl_add_u32 v11, v4, 2, s51
	s_mov_b32 s2, 0
	s_mov_b64 s[72:73], 0
	v_mov_b64_e32 v[6:7], v[4:5]

.LBB0_515:
	s_waitcnt vmcnt(0)
	s_add_i32 s15, s15, 0x10000
	s_cmp_eq_u32 s24, s3
	v_add_u32_e32 v226, 0xfffffe00, v226
	s_waitcnt vmcnt(0) lgkmcnt(0)
	s_barrier
	s_cbranch_scc0 .LBB0_498
	s_and_saveexec_b64 s[0:1], s[6:7]
	ds_write_b32 v222, v147 offset:128
	s_or_b64 exec, exec, s[0:1]
	s_waitcnt lgkmcnt(0)
	v_lshl_add_u32 v3, v211, 4, s2
	ds_read_b32 v4, v3 offset:128
	s_lshl_b32 s0, s66, 14
	v_lshlrev_b32_e32 v5, 2, v212
	v_lshlrev_b32_e32 v6, 11, v211
	s_add_i32 s0, s0, 0
	s_waitcnt lgkmcnt(0)
	v_rcp_f32_e32 v4, v4
	v_add3_u32 v6, s0, v5, v6
	v_add_u32_e32 v14, 0x3000, v6
	v_or_b32_e32 v48, 64, v213
	v_mul_f32_e32 v5, v130, v4
	v_mul_f32_e32 v7, v114, v4
	ds_write2_b32 v6, v5, v7 offset1:32
	v_mul_f32_e32 v5, v98, v4
	v_mul_f32_e32 v4, v82, v4
	ds_write2_b32 v6, v5, v4 offset0:64 offset1:96
	ds_read_b32 v4, v3 offset:132
	v_or_b32_e32 v49, 0x80, v213
	s_lshl_b32 s20, s20, 1
	v_and_b32_e32 v38, 0x78, v210
	v_mov_b32_e32 v13, v2
	s_waitcnt lgkmcnt(0)
	v_rcp_f32_e32 v4, v4
	v_or_b32_e32 v50, 0x100, v213
	v_or_b32_e32 v51, 0x140, v213
	v_or_b32_e32 v52, 0x180, v213
	v_mul_f32_e32 v5, v131, v4
	v_mul_f32_e32 v7, v115, v4
	v_mul_f32_e32 v8, v99, v4
	v_mul_f32_e32 v4, v83, v4
	ds_write2_b32 v6, v5, v7 offset0:128 offset1:160
	ds_write2_b32 v6, v8, v4 offset0:192 offset1:224
	ds_read_b32 v4, v3 offset:136
	v_add_u32_e32 v5, 0x400, v6
	v_or_b32_e32 v53, 0x1c0, v213
	s_waitcnt lgkmcnt(0)
	v_rcp_f32_e32 v4, v4
	s_nop 0
	v_mul_f32_e32 v7, v132, v4
	v_mul_f32_e32 v8, v116, v4
	v_mul_f32_e32 v9, v100, v4
	v_mul_f32_e32 v4, v84, v4
	ds_write2_b32 v5, v7, v8 offset1:32
	ds_write2_b32 v5, v9, v4 offset0:64 offset1:96
	ds_read_b32 v4, v3 offset:140
	s_waitcnt lgkmcnt(0)
	v_rcp_f32_e32 v4, v4
	s_nop 0
	v_mul_f32_e32 v7, v133, v4
	v_mul_f32_e32 v8, v117, v4
	v_mul_f32_e32 v9, v101, v4
	v_mul_f32_e32 v4, v85, v4
	ds_write2_b32 v5, v7, v8 offset0:128 offset1:160
	ds_write2_b32 v5, v9, v4 offset0:192 offset1:224
	ds_read_b32 v4, v3 offset:160
	v_add_u32_e32 v5, 0x1000, v6
	s_waitcnt lgkmcnt(0)
	v_rcp_f32_e32 v4, v4
	s_nop 0
	v_mul_f32_e32 v7, v134, v4
	v_mul_f32_e32 v8, v118, v4
	v_mul_f32_e32 v9, v102, v4
	v_mul_f32_e32 v4, v86, v4
	ds_write2_b32 v5, v7, v8 offset1:32
	ds_write2_b32 v5, v9, v4 offset0:64 offset1:96
	ds_read_b32 v4, v3 offset:164
	s_waitcnt lgkmcnt(0)
	v_rcp_f32_e32 v4, v4
	s_nop 0
	v_mul_f32_e32 v7, v135, v4
	v_mul_f32_e32 v8, v119, v4
	v_mul_f32_e32 v9, v103, v4
	v_mul_f32_e32 v4, v87, v4
	ds_write2_b32 v5, v7, v8 offset0:128 offset1:160
	ds_write2_b32 v5, v9, v4 offset0:192 offset1:224
	ds_read_b32 v4, v3 offset:168
	v_add_u32_e32 v5, 0x1400, v6
	s_waitcnt lgkmcnt(0)
	v_rcp_f32_e32 v4, v4
	s_nop 0
	v_mul_f32_e32 v7, v136, v4
	v_mul_f32_e32 v8, v120, v4
	v_mul_f32_e32 v9, v104, v4
	v_mul_f32_e32 v4, v88, v4
	ds_write2_b32 v5, v7, v8 offset1:32
	ds_write2_b32 v5, v9, v4 offset0:64 offset1:96
	ds_read_b32 v4, v3 offset:172
	s_waitcnt lgkmcnt(0)
	v_rcp_f32_e32 v4, v4
	s_nop 0
	v_mul_f32_e32 v7, v137, v4
	v_mul_f32_e32 v8, v121, v4
	v_mul_f32_e32 v9, v105, v4
	v_mul_f32_e32 v4, v89, v4
	ds_write2_b32 v5, v7, v8 offset0:128 offset1:160
	ds_write2_b32 v5, v9, v4 offset0:192 offset1:224
	ds_read_b32 v4, v3 offset:192
	v_add_u32_e32 v5, 0x2000, v6
	s_waitcnt lgkmcnt(0)
	v_rcp_f32_e32 v4, v4
	s_nop 0
	v_mul_f32_e32 v7, v138, v4
	v_mul_f32_e32 v8, v122, v4
	v_mul_f32_e32 v9, v106, v4
	v_mul_f32_e32 v4, v90, v4
	ds_write2_b32 v5, v7, v8 offset1:32
	ds_write2_b32 v5, v9, v4 offset0:64 offset1:96
	ds_read_b32 v4, v3 offset:196
	s_waitcnt lgkmcnt(0)
	v_rcp_f32_e32 v4, v4
	s_nop 0
	v_mul_f32_e32 v7, v139, v4
	v_mul_f32_e32 v8, v123, v4
	v_mul_f32_e32 v9, v107, v4
	v_mul_f32_e32 v4, v91, v4
	ds_write2_b32 v5, v7, v8 offset0:128 offset1:160
	ds_write2_b32 v5, v9, v4 offset0:192 offset1:224
	ds_read_b32 v4, v3 offset:200
	v_add_u32_e32 v7, 0x2400, v6
	s_waitcnt lgkmcnt(0)
	v_rcp_f32_e32 v4, v4
	s_nop 0
	v_mul_f32_e32 v5, v140, v4
	v_mul_f32_e32 v8, v124, v4
	v_mul_f32_e32 v9, v108, v4
	v_mul_f32_e32 v4, v92, v4
	ds_write2_b32 v7, v5, v8 offset1:32
	ds_write2_b32 v7, v9, v4 offset0:64 offset1:96
	ds_read_b32 v4, v3 offset:204
	v_and_or_b32 v8, v199, 24, s5
	v_add_u32_e32 v8, s66, v8
	s_waitcnt lgkmcnt(0)
	v_rcp_f32_e32 v9, v4
	v_mov_b64_e32 v[4:5], s[68:69]
	v_mul_f32_e32 v10, v141, v9
	v_mul_f32_e32 v11, v125, v9
	v_mul_f32_e32 v12, v109, v9
	v_mul_f32_e32 v9, v93, v9
	ds_write2_b32 v7, v10, v11 offset0:128 offset1:160
	ds_write2_b32 v7, v12, v9 offset0:192 offset1:224
	ds_read_b32 v7, v3 offset:224
	v_lshrrev_b32_e32 v10, 1, v48
	v_lshrrev_b32_e32 v11, 1, v49
	v_and_or_b32 v10, v10, 56, s5
	v_and_b32_e32 v11, 0x58, v11
	s_waitcnt lgkmcnt(0)
	v_rcp_f32_e32 v7, v7
	v_lshlrev_b32_e32 v12, 1, v38
	v_mul_f32_e32 v9, v142, v7
	v_mul_f32_e32 v15, v126, v7
	v_mul_f32_e32 v16, v110, v7
	v_mul_f32_e32 v7, v94, v7
	ds_write2_b32 v14, v9, v15 offset1:32
	ds_write2_b32 v14, v16, v7 offset0:64 offset1:96
	ds_read_b32 v7, v3 offset:228
	v_mad_i64_i32 v[8:9], s[2:3], v8, s19, v[4:5]
	v_add_u32_e32 v15, 0x3400, v6
	s_waitcnt lgkmcnt(0)
	v_rcp_f32_e32 v16, v7
	v_lshl_add_u64 v[6:7], v[8:9], 0, s[20:21]
	v_add_u32_e32 v8, s66, v10
	v_or_b32_e32 v10, s5, v11
	v_mul_f32_e32 v9, v143, v16
	v_mul_f32_e32 v11, v127, v16
	v_mul_f32_e32 v17, v111, v16
	v_mul_f32_e32 v16, v95, v16
	ds_write2_b32 v14, v9, v11 offset0:128 offset1:160
	ds_write2_b32 v14, v17, v16 offset0:192 offset1:224
	ds_read_b32 v11, v3 offset:232
	v_lshl_add_u64 v[6:7], v[6:7], 0, v[12:13]
	v_mad_i64_i32 v[8:9], s[2:3], v8, s19, v[4:5]
	v_add_co_u32_e32 v6, vcc, s50, v6
	s_waitcnt lgkmcnt(0)
	v_rcp_f32_e32 v11, v11
	v_lshl_add_u64 v[8:9], v[8:9], 0, s[20:21]
	v_addc_co_u32_e32 v7, vcc, 0, v7, vcc
	v_mul_f32_e32 v14, v144, v11
	v_mul_f32_e32 v16, v128, v11
	v_mul_f32_e32 v17, v112, v11
	v_mul_f32_e32 v11, v96, v11
	ds_write2_b32 v15, v14, v16 offset1:32
	ds_write2_b32 v15, v17, v11 offset0:64 offset1:96
	ds_read_b32 v3, v3 offset:236
	v_lshl_add_u64 v[8:9], v[8:9], 0, v[12:13]
	v_add_co_u32_e32 v8, vcc, s50, v8
	v_add_u32_e32 v10, s66, v10
	s_waitcnt lgkmcnt(0)
	v_rcp_f32_e32 v3, v3
	v_addc_co_u32_e32 v9, vcc, 0, v9, vcc
	v_mad_i64_i32 v[10:11], s[2:3], v10, s19, v[4:5]
	v_mul_f32_e32 v14, v145, v3
	v_mul_f32_e32 v16, v129, v3
	v_mul_f32_e32 v17, v113, v3
	v_mul_f32_e32 v3, v97, v3
	ds_write2_b32 v15, v14, v16 offset0:128 offset1:160
	ds_write2_b32 v15, v17, v3 offset0:192 offset1:224
	s_waitcnt lgkmcnt(0)
	v_or_b32_e32 v3, 0xc0, v213
	global_load_dwordx4 v[14:17], v[6:7], off offset:1024
	global_load_dwordx4 v[18:21], v[8:9], off offset:1024
	v_lshrrev_b32_e32 v8, 1, v3
	v_and_b32_e32 v8, 0x78, v8
	v_or_b32_e32 v8, s5, v8
	v_lshl_add_u64 v[6:7], v[10:11], 0, s[20:21]
	v_add_u32_e32 v8, s66, v8
	v_lshl_add_u64 v[6:7], v[6:7], 0, v[12:13]
	v_mad_i64_i32 v[8:9], s[2:3], v8, s19, v[4:5]
	v_add_co_u32_e32 v6, vcc, s50, v6
	v_lshl_add_u64 v[8:9], v[8:9], 0, s[20:21]
	s_nop 0
	v_addc_co_u32_e32 v7, vcc, 0, v7, vcc
	v_lshl_add_u64 v[8:9], v[8:9], 0, v[12:13]
	v_add_co_u32_e32 v8, vcc, s50, v8
	s_nop 1
	v_addc_co_u32_e32 v9, vcc, 0, v9, vcc
	global_load_dwordx4 v[22:25], v[6:7], off offset:1024
	global_load_dwordx4 v[26:29], v[8:9], off offset:1024
	v_lshrrev_b32_e32 v6, 1, v50
	v_and_b32_e32 v6, 0x98, v6
	v_or_b32_e32 v6, s5, v6
	v_lshrrev_b32_e32 v8, 1, v51
	v_add_u32_e32 v6, s66, v6
	v_and_b32_e32 v8, 0xb8, v8
	v_mad_i64_i32 v[6:7], s[2:3], v6, s19, v[4:5]
	v_or_b32_e32 v8, s5, v8
	v_lshl_add_u64 v[6:7], v[6:7], 0, s[20:21]
	v_add_u32_e32 v8, s66, v8
	v_lshl_add_u64 v[6:7], v[6:7], 0, v[12:13]
	v_mad_i64_i32 v[8:9], s[2:3], v8, s19, v[4:5]
	v_add_co_u32_e32 v6, vcc, s50, v6
	v_lshl_add_u64 v[8:9], v[8:9], 0, s[20:21]
	s_nop 0
	v_addc_co_u32_e32 v7, vcc, 0, v7, vcc
	v_lshl_add_u64 v[8:9], v[8:9], 0, v[12:13]
	v_add_co_u32_e32 v8, vcc, s50, v8
	s_nop 1
	v_addc_co_u32_e32 v9, vcc, 0, v9, vcc
	global_load_dwordx4 v[30:33], v[6:7], off offset:1024
	global_load_dwordx4 v[34:37], v[8:9], off offset:1024
	v_lshrrev_b32_e32 v6, 1, v52
	v_and_b32_e32 v6, 0xd8, v6
	v_or_b32_e32 v6, s5, v6
	v_lshrrev_b32_e32 v8, 1, v53
	v_add_u32_e32 v6, s66, v6
	v_and_b32_e32 v8, 0xf8, v8
	v_mad_i64_i32 v[6:7], s[2:3], v6, s19, v[4:5]
	v_or_b32_e32 v8, s5, v8
	v_lshl_add_u64 v[6:7], v[6:7], 0, s[20:21]
	v_add_u32_e32 v8, s66, v8
	v_lshl_add_u64 v[6:7], v[6:7], 0, v[12:13]
	v_mad_i64_i32 v[4:5], s[2:3], v8, s19, v[4:5]
	v_add_co_u32_e32 v6, vcc, s50, v6
	v_lshl_add_u64 v[4:5], v[4:5], 0, s[20:21]
	s_nop 0
	v_addc_co_u32_e32 v7, vcc, 0, v7, vcc
	v_lshl_add_u64 v[4:5], v[4:5], 0, v[12:13]
	v_add_co_u32_e32 v4, vcc, s50, v4
	s_nop 1
	v_addc_co_u32_e32 v5, vcc, 0, v5, vcc
	global_load_dwordx4 v[8:11], v[6:7], off offset:1024
	s_nop 0
	global_load_dwordx4 v[4:7], v[4:5], off offset:1024
	v_lshl_add_u32 v54, v38, 2, s0
	v_lshl_add_u32 v44, v197, 9, v54
	ds_read_b128 v[38:41], v44
	v_lshl_or_b32 v42, v197, 3, s5
	v_mov_b32_e32 v43, v2
	v_lshl_add_u64 v[46:47], v[42:43], 0, s[66:67]
	ds_read_b128 v[42:45], v44 offset:16
	s_waitcnt vmcnt(7)
	v_lshlrev_b32_e32 v55, 16, v14
	v_and_b32_e32 v14, 0xffff0000, v14
	s_waitcnt lgkmcnt(1)
	v_mul_f32_e32 v38, v38, v55
	v_mul_f32_e32 v14, v39, v14
	v_cvt_pk_bf16_f32 v14, v38, v14
	v_lshlrev_b32_e32 v38, 16, v15
	v_and_b32_e32 v15, 0xffff0000, v15
	v_mul_f32_e32 v38, v40, v38
	v_mul_f32_e32 v15, v41, v15
	v_cvt_pk_bf16_f32 v15, v38, v15
	v_lshlrev_b32_e32 v38, 16, v16
	v_and_b32_e32 v16, 0xffff0000, v16
	s_add_u32 s0, s36, s20
	s_waitcnt lgkmcnt(0)
	v_mul_f32_e32 v38, v42, v38
	v_mul_f32_e32 v16, v43, v16
	s_addc_u32 s1, s37, 0
	v_cvt_pk_bf16_f32 v16, v38, v16
	v_lshlrev_b32_e32 v38, 16, v17
	v_and_b32_e32 v17, 0xffff0000, v17
	v_lshl_add_u64 v[12:13], s[0:1], 0, v[12:13]
	s_mov_b64 s[0:1], 0xc600000
	v_mul_f32_e32 v38, v44, v38
	v_mul_f32_e32 v17, v45, v17
	v_lshl_add_u64 v[12:13], v[12:13], 0, s[0:1]
	v_cvt_pk_bf16_f32 v17, v38, v17
	v_lshlrev_b64 v[38:39], 12, v[46:47]
	v_lshl_add_u64 v[38:39], v[12:13], 0, v[38:39]
	global_store_dwordx4 v[38:39], v[14:17], off sc0 sc1
	v_mov_b32_e32 v39, v2
	s_waitcnt vmcnt(7)
	v_lshlrev_b32_e32 v44, 16, v18
	v_lshrrev_b32_e32 v14, 4, v48
	v_lshl_add_u32 v40, v14, 9, v54
	v_lshl_or_b32 v38, v14, 3, s5
	ds_read_b128 v[14:17], v40
	v_and_b32_e32 v18, 0xffff0000, v18
	v_lshl_add_u64 v[42:43], v[38:39], 0, s[66:67]
	ds_read_b128 v[38:41], v40 offset:16
	v_lshrrev_b32_e32 v3, 4, v3
	s_waitcnt lgkmcnt(1)
	v_mul_f32_e32 v14, v14, v44
	v_mul_f32_e32 v15, v15, v18
	v_cvt_pk_bf16_f32 v14, v14, v15
	v_lshlrev_b32_e32 v15, 16, v19
	v_mul_f32_e32 v15, v16, v15
	v_and_b32_e32 v16, 0xffff0000, v19
	v_mul_f32_e32 v16, v17, v16
	v_cvt_pk_bf16_f32 v15, v15, v16
	v_lshlrev_b32_e32 v16, 16, v20
	v_and_b32_e32 v17, 0xffff0000, v20
	s_waitcnt lgkmcnt(0)
	v_mul_f32_e32 v16, v38, v16
	v_mul_f32_e32 v17, v39, v17
	v_cvt_pk_bf16_f32 v16, v16, v17
	v_lshlrev_b32_e32 v17, 16, v21
	v_and_b32_e32 v18, 0xffff0000, v21
	v_mul_f32_e32 v17, v40, v17
	v_mul_f32_e32 v18, v41, v18
	v_cvt_pk_bf16_f32 v17, v17, v18
	v_lshlrev_b64 v[18:19], 12, v[42:43]
	v_lshl_add_u64 v[18:19], v[12:13], 0, v[18:19]
	global_store_dwordx4 v[18:19], v[14:17], off sc0 sc1
	v_mov_b32_e32 v19, v2
	s_waitcnt vmcnt(7)
	v_lshlrev_b32_e32 v40, 16, v22
	v_lshrrev_b32_e32 v14, 4, v49
	v_lshl_add_u32 v20, v14, 9, v54
	v_lshl_or_b32 v18, v14, 3, s5
	ds_read_b128 v[14:17], v20
	v_and_b32_e32 v22, 0xffff0000, v22
	v_lshl_add_u64 v[38:39], v[18:19], 0, s[66:67]
	ds_read_b128 v[18:21], v20 offset:16
	s_movk_i32 s6, 0x4000
	s_waitcnt lgkmcnt(1)
	v_mul_f32_e32 v14, v14, v40
	v_mul_f32_e32 v15, v15, v22
	v_cvt_pk_bf16_f32 v14, v14, v15
	v_lshlrev_b32_e32 v15, 16, v23
	v_mul_f32_e32 v15, v16, v15
	v_and_b32_e32 v16, 0xffff0000, v23
	v_mul_f32_e32 v16, v17, v16
	v_cvt_pk_bf16_f32 v15, v15, v16
	v_lshlrev_b32_e32 v16, 16, v24
	v_and_b32_e32 v17, 0xffff0000, v24
	s_waitcnt lgkmcnt(0)
	v_mul_f32_e32 v16, v18, v16
	v_mul_f32_e32 v17, v19, v17
	v_cvt_pk_bf16_f32 v16, v16, v17
	v_lshlrev_b32_e32 v17, 16, v25
	v_and_b32_e32 v18, 0xffff0000, v25
	v_mul_f32_e32 v17, v20, v17
	v_mul_f32_e32 v18, v21, v18
	v_cvt_pk_bf16_f32 v17, v17, v18
	v_lshlrev_b64 v[18:19], 12, v[38:39]
	v_lshl_add_u64 v[18:19], v[12:13], 0, v[18:19]
	global_store_dwordx4 v[18:19], v[14:17], off sc0 sc1
	v_lshl_or_b32 v18, v3, 3, s5
	v_lshl_add_u32 v3, v3, 9, v54
	ds_read_b128 v[14:17], v3
	v_mov_b32_e32 v19, v2
	v_lshl_add_u64 v[22:23], v[18:19], 0, s[66:67]
	ds_read_b128 v[18:21], v3 offset:16
	s_waitcnt vmcnt(7)
	v_lshlrev_b32_e32 v3, 16, v26
	s_waitcnt lgkmcnt(1)
	v_mul_f32_e32 v3, v14, v3
	v_and_b32_e32 v14, 0xffff0000, v26
	v_mul_f32_e32 v14, v15, v14
	v_cvt_pk_bf16_f32 v14, v3, v14
	v_lshlrev_b32_e32 v3, 16, v27
	v_and_b32_e32 v15, 0xffff0000, v27
	v_mul_f32_e32 v3, v16, v3
	v_mul_f32_e32 v15, v17, v15
	v_cvt_pk_bf16_f32 v15, v3, v15
	v_lshlrev_b32_e32 v3, 16, v28
	v_and_b32_e32 v16, 0xffff0000, v28
	s_waitcnt lgkmcnt(0)
	v_mul_f32_e32 v3, v18, v3
	v_mul_f32_e32 v16, v19, v16
	v_cvt_pk_bf16_f32 v16, v3, v16
	v_lshlrev_b32_e32 v3, 16, v29
	v_and_b32_e32 v17, 0xffff0000, v29
	v_mul_f32_e32 v3, v20, v3
	v_mul_f32_e32 v17, v21, v17
	v_lshlrev_b64 v[18:19], 12, v[22:23]
	v_cvt_pk_bf16_f32 v17, v3, v17
	v_lshl_add_u64 v[18:19], v[12:13], 0, v[18:19]
	v_lshrrev_b32_e32 v3, 4, v50
	global_store_dwordx4 v[18:19], v[14:17], off sc0 sc1
	v_lshl_or_b32 v18, v3, 3, s5
	v_lshl_add_u32 v3, v3, 9, v54
	ds_read_b128 v[14:17], v3
	v_mov_b32_e32 v19, v2
	v_lshl_add_u64 v[22:23], v[18:19], 0, s[66:67]
	ds_read_b128 v[18:21], v3 offset:16
	s_waitcnt vmcnt(7)
	v_lshlrev_b32_e32 v3, 16, v30
	s_waitcnt lgkmcnt(1)
	v_mul_f32_e32 v3, v14, v3
	v_and_b32_e32 v14, 0xffff0000, v30
	v_mul_f32_e32 v14, v15, v14
	v_cvt_pk_bf16_f32 v14, v3, v14
	v_lshlrev_b32_e32 v3, 16, v31
	v_and_b32_e32 v15, 0xffff0000, v31
	v_mul_f32_e32 v3, v16, v3
	v_mul_f32_e32 v15, v17, v15
	v_cvt_pk_bf16_f32 v15, v3, v15
	v_lshlrev_b32_e32 v3, 16, v32
	v_and_b32_e32 v16, 0xffff0000, v32
	s_waitcnt lgkmcnt(0)
	v_mul_f32_e32 v3, v18, v3
	v_mul_f32_e32 v16, v19, v16
	v_cvt_pk_bf16_f32 v16, v3, v16
	v_lshlrev_b32_e32 v3, 16, v33
	v_and_b32_e32 v17, 0xffff0000, v33
	v_mul_f32_e32 v3, v20, v3
	v_mul_f32_e32 v17, v21, v17
	v_lshlrev_b64 v[18:19], 12, v[22:23]
	v_cvt_pk_bf16_f32 v17, v3, v17
	v_lshl_add_u64 v[18:19], v[12:13], 0, v[18:19]
	v_lshrrev_b32_e32 v3, 4, v51
	global_store_dwordx4 v[18:19], v[14:17], off sc0 sc1
	v_lshl_or_b32 v18, v3, 3, s5
	v_lshl_add_u32 v3, v3, 9, v54
	ds_read_b128 v[14:17], v3
	v_mov_b32_e32 v19, v2
	v_lshl_add_u64 v[22:23], v[18:19], 0, s[66:67]
	ds_read_b128 v[18:21], v3 offset:16
	s_waitcnt vmcnt(7)
	v_lshlrev_b32_e32 v3, 16, v34
	s_waitcnt lgkmcnt(1)
	v_mul_f32_e32 v3, v14, v3
	v_and_b32_e32 v14, 0xffff0000, v34
	v_mul_f32_e32 v14, v15, v14
	v_cvt_pk_bf16_f32 v14, v3, v14
	v_lshlrev_b32_e32 v3, 16, v35
	v_and_b32_e32 v15, 0xffff0000, v35
	v_mul_f32_e32 v3, v16, v3
	v_mul_f32_e32 v15, v17, v15
	v_cvt_pk_bf16_f32 v15, v3, v15
	v_lshlrev_b32_e32 v3, 16, v36
	v_and_b32_e32 v16, 0xffff0000, v36
	s_waitcnt lgkmcnt(0)
	v_mul_f32_e32 v3, v18, v3
	v_mul_f32_e32 v16, v19, v16
	v_cvt_pk_bf16_f32 v16, v3, v16
	v_lshlrev_b32_e32 v3, 16, v37
	v_and_b32_e32 v17, 0xffff0000, v37
	v_mul_f32_e32 v3, v20, v3
	v_mul_f32_e32 v17, v21, v17
	v_lshlrev_b64 v[18:19], 12, v[22:23]
	v_cvt_pk_bf16_f32 v17, v3, v17
	v_lshl_add_u64 v[18:19], v[12:13], 0, v[18:19]
	v_lshrrev_b32_e32 v3, 4, v52
	global_store_dwordx4 v[18:19], v[14:17], off sc0 sc1
	v_lshl_or_b32 v18, v3, 3, s5
	v_lshl_add_u32 v3, v3, 9, v54
	ds_read_b128 v[14:17], v3
	v_mov_b32_e32 v19, v2
	v_lshl_add_u64 v[22:23], v[18:19], 0, s[66:67]
	ds_read_b128 v[18:21], v3 offset:16
	s_waitcnt vmcnt(7)
	v_lshlrev_b32_e32 v3, 16, v8
	v_and_b32_e32 v8, 0xffff0000, v8
	s_waitcnt lgkmcnt(1)
	v_mul_f32_e32 v3, v14, v3
	v_mul_f32_e32 v8, v15, v8
	v_cvt_pk_bf16_f32 v8, v3, v8
	v_lshlrev_b32_e32 v3, 16, v9
	v_and_b32_e32 v9, 0xffff0000, v9
	v_mul_f32_e32 v3, v16, v3
	v_mul_f32_e32 v9, v17, v9
	v_cvt_pk_bf16_f32 v9, v3, v9
	v_lshlrev_b32_e32 v3, 16, v10
	v_and_b32_e32 v10, 0xffff0000, v10
	s_waitcnt lgkmcnt(0)
	v_mul_f32_e32 v3, v18, v3
	v_mul_f32_e32 v10, v19, v10
	v_cvt_pk_bf16_f32 v10, v3, v10
	v_lshlrev_b32_e32 v3, 16, v11
	v_and_b32_e32 v11, 0xffff0000, v11
	v_mul_f32_e32 v3, v20, v3
	v_mul_f32_e32 v11, v21, v11
	v_lshlrev_b64 v[14:15], 12, v[22:23]
	v_cvt_pk_bf16_f32 v11, v3, v11
	v_lshl_add_u64 v[14:15], v[12:13], 0, v[14:15]
	v_lshrrev_b32_e32 v3, 4, v53
	global_store_dwordx4 v[14:15], v[8:11], off sc0 sc1
	v_lshl_or_b32 v14, v3, 3, s5
	v_lshl_add_u32 v3, v3, 9, v54
	ds_read_b128 v[8:11], v3
	v_mov_b32_e32 v15, v2
	v_lshl_add_u64 v[18:19], v[14:15], 0, s[66:67]
	ds_read_b128 v[14:17], v3 offset:16
	s_waitcnt vmcnt(7)
	v_lshlrev_b32_e32 v3, 16, v4
	v_and_b32_e32 v4, 0xffff0000, v4
	s_waitcnt lgkmcnt(1)
	v_mul_f32_e32 v3, v8, v3
	v_mul_f32_e32 v4, v9, v4
	v_cvt_pk_bf16_f32 v4, v3, v4
	v_lshlrev_b32_e32 v3, 16, v5
	v_and_b32_e32 v5, 0xffff0000, v5
	v_mul_f32_e32 v3, v10, v3
	v_mul_f32_e32 v5, v11, v5
	v_cvt_pk_bf16_f32 v5, v3, v5
	v_lshlrev_b32_e32 v3, 16, v6
	v_and_b32_e32 v6, 0xffff0000, v6
	s_waitcnt lgkmcnt(0)
	v_mul_f32_e32 v3, v14, v3
	v_mul_f32_e32 v6, v15, v6
	v_cvt_pk_bf16_f32 v6, v3, v6
	v_lshlrev_b32_e32 v3, 16, v7
	v_and_b32_e32 v7, 0xffff0000, v7
	v_lshlrev_b64 v[8:9], 12, v[18:19]
	v_mul_f32_e32 v7, v17, v7
	v_lshl_add_u64 v[8:9], v[12:13], 0, v[8:9]
	v_mul_f32_e32 v3, v16, v3
	v_cvt_pk_bf16_f32 v7, v3, v7
	global_store_dwordx4 v[8:9], v[4:7], off sc0 sc1
	s_setprio 0
	s_barrier
	s_mov_b64 s[0:1], 0
